# grid barrier: XCD leaders poll the arrival counter directly (no second generation word round trip)
# speedup vs baseline: 1.0051x; 1.0040x over previous
.LBB0_944:
	s_or_b64 exec, exec, s[10:11]
	s_waitcnt vmcnt(0)
	v_readfirstlane_b32 s0, v4
	v_cvt_f32_u32_e32 v4, v2
	v_sub_u32_e32 v5, 0, v2
	v_add_u32_e32 v3, s0, v3
	v_readlane_b32 s6, v255, 5
	v_rcp_iflag_f32_e32 v4, v4
	v_readlane_b32 s7, v255, 6
	s_mov_b64 s[10:11], 0
	v_mul_f32_e32 v4, 0x4f7ffffe, v4
	v_cvt_u32_f32_e32 v4, v4
	v_mul_lo_u32 v5, v5, v4
	v_mul_hi_u32 v5, v4, v5
	v_add_u32_e32 v4, v4, v5
	v_mul_hi_u32 v4, v3, v4
	v_mul_lo_u32 v5, v4, v2
	v_sub_u32_e32 v5, v3, v5
	v_cmp_ge_u32_e32 vcc, v5, v2
	v_add_u32_e32 v6, 1, v4
	v_add_u32_e32 v3, 1, v3
	v_cndmask_b32_e32 v4, v4, v6, vcc
	v_sub_u32_e32 v6, v5, v2
	v_cndmask_b32_e32 v5, v5, v6, vcc
	v_cmp_ge_u32_e32 vcc, v5, v2
	v_add_u32_e32 v5, 1, v4
	s_nop 0
	v_cndmask_b32_e32 v4, v4, v5, vcc
	v_mul_lo_u32 v5, v2, v4
	v_add_u32_e32 v2, v5, v2
	v_mov_b32_e32 v6, v2
	v_cmp_ne_u32_e32 vcc, v3, v2
	v_mov_b64_e32 v[2:3], s[6:7]
	s_and_saveexec_b64 s[6:7], vcc
	s_cbranch_execz .LBB0_956
	v_readlane_b32 s10, v255, 3
	v_readlane_b32 s11, v255, 4
	s_mov_b64 s[12:13], 0
	s_nop 3
	global_load_dword v2, v99, s[10:11] sc1
	s_waitcnt vmcnt(0)
	v_cmp_lt_u32_e32 vcc, v2, v6
	s_and_saveexec_b64 s[10:11], vcc
	s_cbranch_execz .LBB0_955
	s_mov_b32 s0, 1
	s_branch .LBB0_948

.LBB0_950:
	v_readlane_b32 s16, v255, 3
	v_readlane_b32 s17, v255, 4
	s_add_i32 s0, s0, 1
	s_mov_b64 s[18:19], -1
	s_nop 2
	global_load_dword v2, v99, s[16:17] sc1
	s_waitcnt vmcnt(0)
	v_cmp_ge_u32_e32 vcc, v2, v6
	s_orn2_b64 s[16:17], vcc, exec
	s_branch .LBB0_947
